# FFN-in GEMM: first K iteration peeled with C=0 on each accumulator's first MFMA; 128 zeroing v_mov per tile removed
# speedup vs baseline: 1.0190x; 1.0190x over previous
.LBB0_477:
	s_ashr_i32 s17, s16, 31
	s_lshl_b64 s[18:19], s[16:17], 19
	s_add_u32 s18, s0, s18
	s_addc_u32 s19, s1, s19
	s_and_b64 s[24:25], s[38:39], exec
	s_cselect_b32 s4, s19, s41
	s_cselect_b32 s9, s18, s40
	s_ashr_i32 s85, s84, 31
	s_lshl_b64 s[24:25], s[84:85], 19
	s_add_u32 s82, s80, s24
	s_addc_u32 s83, s81, s25
	s_and_b64 s[24:25], s[38:39], exec
	s_cselect_b32 s17, s83, s13
	s_cselect_b32 s24, s82, s12
	s_add_u32 s40, s40, 0x40080
	s_addc_u32 s41, s41, 0
	s_add_u32 s25, s12, 0x100
	s_addc_u32 s50, s13, 0
	s_mov_b32 s51, -2
	s_add_u32 s12, s40, 0xfffc0080
	s_addc_u32 s13, s41, -1
	s_add_i32 s85, 0, 0x10000
	s_cmp_eq_u32 s51, 12
	s_cselect_b32 s43, s4, s13
	s_cselect_b32 s42, s9, s12
	v_add_u32_e32 v158, s85, v196
	s_cselect_b32 s13, s17, s50
	s_cselect_b32 s12, s24, s25
	s_add_i32 s27, 0, 0x14000
	ds_read_b128 v[150:153], v158
	ds_read_b128 v[154:157], v158 offset:1024
	ds_read_b128 v[170:173], v158 offset:2048
	ds_read_b128 v[174:177], v158 offset:3072
	v_add_u32_e32 v158, s27, v196
	ds_read_b128 v[178:181], v158
	ds_read_b128 v[182:185], v158 offset:1024
	ds_read_b128 v[186:189], v158 offset:2048
	ds_read_b128 v[200:203], v158 offset:3072
	v_lshl_add_u64 v[158:159], s[40:41], 0, v[146:147]
	s_add_i32 m0, s15, 0xc000
	ds_read_b128 v[204:207], v199
	ds_read_b128 v[208:211], v199 offset:1024
	ds_read_b128 v[212:215], v199 offset:2048
	ds_read_b128 v[234:237], v199 offset:3072
	ds_read_b128 v[238:241], v199 offset:4096
	ds_read_b128 v[242:245], v199 offset:5120
	ds_read_b128 v[246:249], v199 offset:6144
	ds_read_b128 v[222:225], v199 offset:7168
	global_load_lds_dwordx4 v[158:159], off
	v_lshl_add_u64 v[158:159], s[40:41], 0, v[148:149]
	s_add_i32 m0, s15, 0xe000
	s_nop 0
	global_load_lds_dwordx4 v[158:159], off
	s_waitcnt vmcnt(8)
	s_waitcnt lgkmcnt(0)
	s_barrier
	s_setprio 1
	s_waitcnt lgkmcnt(0)
	v_mfma_f32_16x16x32_bf16 v[124:127], v[150:153], v[204:207], 0
	v_mfma_f32_16x16x32_bf16 v[120:123], v[170:173], v[204:207], 0
	v_mfma_f32_16x16x32_bf16 v[108:111], v[150:153], v[212:215], 0
	v_mfma_f32_16x16x32_bf16 v[104:107], v[170:173], v[212:215], 0
	v_mfma_f32_16x16x32_bf16 v[92:95], v[150:153], v[238:241], 0
	v_mfma_f32_16x16x32_bf16 v[88:91], v[170:173], v[238:241], 0
	v_mfma_f32_16x16x32_bf16 v[76:79], v[150:153], v[246:249], 0
	v_mfma_f32_16x16x32_bf16 v[72:75], v[170:173], v[246:249], 0
	v_mfma_f32_16x16x32_bf16 v[124:127], v[154:157], v[208:211], v[124:127]
	v_mfma_f32_16x16x32_bf16 v[120:123], v[174:177], v[208:211], v[120:123]
	v_mfma_f32_16x16x32_bf16 v[108:111], v[154:157], v[234:237], v[108:111]
	v_mfma_f32_16x16x32_bf16 v[104:107], v[174:177], v[234:237], v[104:107]
	v_mfma_f32_16x16x32_bf16 v[92:95], v[154:157], v[242:245], v[92:95]
	v_mfma_f32_16x16x32_bf16 v[88:91], v[174:177], v[242:245], v[88:91]
	v_mfma_f32_16x16x32_bf16 v[76:79], v[154:157], v[222:225], v[76:79]
	v_mfma_f32_16x16x32_bf16 v[72:75], v[174:177], v[222:225], v[72:75]
	s_setprio 0
	s_setprio 1
	v_mfma_f32_16x16x32_bf16 v[116:119], v[178:181], v[204:207], 0
	v_mfma_f32_16x16x32_bf16 v[112:115], v[186:189], v[204:207], 0
	v_mfma_f32_16x16x32_bf16 v[100:103], v[178:181], v[212:215], 0
	v_mfma_f32_16x16x32_bf16 v[96:99], v[186:189], v[212:215], 0
	v_mfma_f32_16x16x32_bf16 v[84:87], v[178:181], v[238:241], 0
	v_mfma_f32_16x16x32_bf16 v[80:83], v[186:189], v[238:241], 0
	v_mfma_f32_16x16x32_bf16 v[68:71], v[178:181], v[246:249], 0
	v_mfma_f32_16x16x32_bf16 v[64:67], v[186:189], v[246:249], 0
	v_mfma_f32_16x16x32_bf16 v[116:119], v[182:185], v[208:211], v[116:119]
	v_mfma_f32_16x16x32_bf16 v[112:115], v[200:203], v[208:211], v[112:115]
	v_mfma_f32_16x16x32_bf16 v[100:103], v[182:185], v[234:237], v[100:103]
	v_mfma_f32_16x16x32_bf16 v[96:99], v[200:203], v[234:237], v[96:99]
	v_mfma_f32_16x16x32_bf16 v[84:87], v[182:185], v[242:245], v[84:87]
	v_mfma_f32_16x16x32_bf16 v[80:83], v[200:203], v[242:245], v[80:83]
	v_mfma_f32_16x16x32_bf16 v[68:71], v[182:185], v[222:225], v[68:71]
	v_mfma_f32_16x16x32_bf16 v[64:67], v[200:203], v[222:225], v[64:67]
	s_setprio 0
	s_barrier
	s_add_i32 s85, s85, s86
	v_lshl_add_u64 v[158:159], s[12:13], 0, v[130:131]
	s_mov_b32 m0, s85
	ds_read_b128 v[204:207], v199 offset:16384
	ds_read_b128 v[208:211], v199 offset:17408
	ds_read_b128 v[212:215], v199 offset:18432
	ds_read_b128 v[222:225], v199 offset:19456
	ds_read_b128 v[234:237], v199 offset:20480
	ds_read_b128 v[238:241], v199 offset:21504
	ds_read_b128 v[242:245], v199 offset:22528
	ds_read_b128 v[246:249], v199 offset:23552
	global_load_lds_dwordx4 v[158:159], off
	s_add_i32 m0, s85, 0x2000
	s_add_u32 vcc_lo, s12, 0x40000
	v_lshl_add_u64 v[250:251], s[12:13], 0, v[134:135]
	s_addc_u32 vcc_hi, s13, 0
	s_add_i32 s27, s27, s86
	global_load_lds_dwordx4 v[250:251], off
	v_lshl_add_u64 v[226:227], vcc, 0, v[130:131]
	s_mov_b32 m0, s27
	v_lshl_add_u64 v[162:163], s[42:43], 0, v[132:133]
	global_load_lds_dwordx4 v[226:227], off
	v_lshl_add_u64 v[226:227], vcc, 0, v[134:135]
	s_add_i32 m0, s27, 0x2000
	s_nop 0
	global_load_lds_dwordx4 v[226:227], off
	v_lshl_add_u64 v[226:227], s[42:43], 0, v[128:129]
	s_mov_b32 m0, s15
	s_nop 0
	global_load_lds_dwordx4 v[226:227], off
	s_mov_b32 m0, s87
	s_nop 0
	global_load_lds_dwordx4 v[162:163], off
	s_waitcnt vmcnt(8)
	s_waitcnt lgkmcnt(0)
	s_barrier
	s_setprio 1
	s_waitcnt lgkmcnt(0)
	v_mfma_f32_16x16x32_bf16 v[60:63], v[150:153], v[204:207], 0
	v_mfma_f32_16x16x32_bf16 v[56:59], v[170:173], v[204:207], 0
	v_mfma_f32_16x16x32_bf16 v[44:47], v[150:153], v[212:215], 0
	v_mfma_f32_16x16x32_bf16 v[40:43], v[170:173], v[212:215], 0
	v_mfma_f32_16x16x32_bf16 v[28:31], v[150:153], v[234:237], 0
	v_mfma_f32_16x16x32_bf16 v[24:27], v[170:173], v[234:237], 0
	v_mfma_f32_16x16x32_bf16 v[12:15], v[150:153], v[242:245], 0
	v_mfma_f32_16x16x32_bf16 v[8:11], v[170:173], v[242:245], 0
	v_mfma_f32_16x16x32_bf16 v[60:63], v[154:157], v[208:211], v[60:63]
	v_mfma_f32_16x16x32_bf16 v[56:59], v[174:177], v[208:211], v[56:59]
	v_mfma_f32_16x16x32_bf16 v[44:47], v[154:157], v[222:225], v[44:47]
	v_mfma_f32_16x16x32_bf16 v[40:43], v[174:177], v[222:225], v[40:43]
	v_mfma_f32_16x16x32_bf16 v[28:31], v[154:157], v[238:241], v[28:31]
	v_mfma_f32_16x16x32_bf16 v[24:27], v[174:177], v[238:241], v[24:27]
	v_mfma_f32_16x16x32_bf16 v[12:15], v[154:157], v[246:249], v[12:15]
	v_mfma_f32_16x16x32_bf16 v[8:11], v[174:177], v[246:249], v[8:11]
	s_setprio 0
	s_setprio 1
	v_mfma_f32_16x16x32_bf16 v[52:55], v[178:181], v[204:207], 0
	v_mfma_f32_16x16x32_bf16 v[48:51], v[186:189], v[204:207], 0
	v_mfma_f32_16x16x32_bf16 v[36:39], v[178:181], v[212:215], 0
	v_mfma_f32_16x16x32_bf16 v[32:35], v[186:189], v[212:215], 0
	v_mfma_f32_16x16x32_bf16 v[20:23], v[178:181], v[234:237], 0
	v_mfma_f32_16x16x32_bf16 v[16:19], v[186:189], v[234:237], 0
	v_mfma_f32_16x16x32_bf16 v[4:7], v[178:181], v[242:245], 0
	v_mfma_f32_16x16x32_bf16 v[0:3], v[186:189], v[242:245], 0
	v_mfma_f32_16x16x32_bf16 v[52:55], v[182:185], v[208:211], v[52:55]
	v_mfma_f32_16x16x32_bf16 v[48:51], v[200:203], v[208:211], v[48:51]
	v_mfma_f32_16x16x32_bf16 v[36:39], v[182:185], v[222:225], v[36:39]
	v_mfma_f32_16x16x32_bf16 v[32:35], v[200:203], v[222:225], v[32:35]
	v_mfma_f32_16x16x32_bf16 v[20:23], v[182:185], v[238:241], v[20:23]
	v_mfma_f32_16x16x32_bf16 v[16:19], v[200:203], v[238:241], v[16:19]
	v_mfma_f32_16x16x32_bf16 v[4:7], v[182:185], v[246:249], v[4:7]
	v_mfma_f32_16x16x32_bf16 v[0:3], v[200:203], v[246:249], v[0:3]
	s_setprio 0
	s_barrier
	s_add_i32 s27, 0, 0x18000
	v_add_u32_e32 v160, s27, v196
	s_add_i32 s85, 0, 0x1c000
	ds_read_b128 v[150:153], v160
	ds_read_b128 v[154:157], v160 offset:1024
	ds_read_b128 v[170:173], v160 offset:2048
	ds_read_b128 v[174:177], v160 offset:3072
	v_add_u32_e32 v160, s85, v196
	ds_read_b128 v[178:181], v160
	ds_read_b128 v[182:185], v160 offset:1024
	ds_read_b128 v[186:189], v160 offset:2048
	ds_read_b128 v[200:203], v160 offset:3072
	s_add_u32 s42, s42, 0x40000
	s_addc_u32 s43, s43, 0
	s_mov_b32 m0, s88
	v_lshl_add_u64 v[164:165], s[42:43], 0, v[128:129]
	ds_read_b128 v[204:207], v199 offset:32768
	ds_read_b128 v[208:211], v199 offset:33792
	ds_read_b128 v[212:215], v199 offset:34816
	ds_read_b128 v[222:225], v199 offset:35840
	ds_read_b128 v[234:237], v199 offset:36864
	ds_read_b128 v[238:241], v199 offset:37888
	ds_read_b128 v[242:245], v199 offset:38912
	ds_read_b128 v[246:249], v199 offset:39936
	global_load_lds_dwordx4 v[164:165], off
	v_lshl_add_u64 v[164:165], s[42:43], 0, v[132:133]
	s_mov_b32 m0, s89
	s_nop 0
	global_load_lds_dwordx4 v[164:165], off
	s_waitcnt vmcnt(8)
	s_waitcnt lgkmcnt(0)
	s_barrier
	s_setprio 1
	s_waitcnt lgkmcnt(0)
	v_mfma_f32_16x16x32_bf16 v[124:127], v[150:153], v[204:207], v[124:127]
	v_mfma_f32_16x16x32_bf16 v[120:123], v[170:173], v[204:207], v[120:123]
	v_mfma_f32_16x16x32_bf16 v[108:111], v[150:153], v[212:215], v[108:111]
	v_mfma_f32_16x16x32_bf16 v[104:107], v[170:173], v[212:215], v[104:107]
	v_mfma_f32_16x16x32_bf16 v[92:95], v[150:153], v[234:237], v[92:95]
	v_mfma_f32_16x16x32_bf16 v[88:91], v[170:173], v[234:237], v[88:91]
	v_mfma_f32_16x16x32_bf16 v[76:79], v[150:153], v[242:245], v[76:79]
	v_mfma_f32_16x16x32_bf16 v[72:75], v[170:173], v[242:245], v[72:75]
	v_mfma_f32_16x16x32_bf16 v[124:127], v[154:157], v[208:211], v[124:127]
	v_mfma_f32_16x16x32_bf16 v[120:123], v[174:177], v[208:211], v[120:123]
	v_mfma_f32_16x16x32_bf16 v[108:111], v[154:157], v[222:225], v[108:111]
	v_mfma_f32_16x16x32_bf16 v[104:107], v[174:177], v[222:225], v[104:107]
	v_mfma_f32_16x16x32_bf16 v[92:95], v[154:157], v[238:241], v[92:95]
	v_mfma_f32_16x16x32_bf16 v[88:91], v[174:177], v[238:241], v[88:91]
	v_mfma_f32_16x16x32_bf16 v[76:79], v[154:157], v[246:249], v[76:79]
	v_mfma_f32_16x16x32_bf16 v[72:75], v[174:177], v[246:249], v[72:75]
	s_setprio 0
	s_setprio 1
	v_mfma_f32_16x16x32_bf16 v[116:119], v[178:181], v[204:207], v[116:119]
	v_mfma_f32_16x16x32_bf16 v[112:115], v[186:189], v[204:207], v[112:115]
	v_mfma_f32_16x16x32_bf16 v[100:103], v[178:181], v[212:215], v[100:103]
	v_mfma_f32_16x16x32_bf16 v[96:99], v[186:189], v[212:215], v[96:99]
	v_mfma_f32_16x16x32_bf16 v[84:87], v[178:181], v[234:237], v[84:87]
	v_mfma_f32_16x16x32_bf16 v[80:83], v[186:189], v[234:237], v[80:83]
	v_mfma_f32_16x16x32_bf16 v[68:71], v[178:181], v[242:245], v[68:71]
	v_mfma_f32_16x16x32_bf16 v[64:67], v[186:189], v[242:245], v[64:67]
	v_mfma_f32_16x16x32_bf16 v[116:119], v[182:185], v[208:211], v[116:119]
	v_mfma_f32_16x16x32_bf16 v[112:115], v[200:203], v[208:211], v[112:115]
	v_mfma_f32_16x16x32_bf16 v[100:103], v[182:185], v[222:225], v[100:103]
	v_mfma_f32_16x16x32_bf16 v[96:99], v[200:203], v[222:225], v[96:99]
	v_mfma_f32_16x16x32_bf16 v[84:87], v[182:185], v[238:241], v[84:87]
	v_mfma_f32_16x16x32_bf16 v[80:83], v[200:203], v[238:241], v[80:83]
	v_mfma_f32_16x16x32_bf16 v[68:71], v[182:185], v[246:249], v[68:71]
	v_mfma_f32_16x16x32_bf16 v[64:67], v[200:203], v[246:249], v[64:67]
	s_setprio 0
	s_barrier
	s_add_i32 s27, s27, s86
	v_lshl_add_u64 v[158:159], v[158:159], 0, s[48:49]
	s_mov_b32 m0, s27
	ds_read_b128 v[204:207], v199 offset:49152
	ds_read_b128 v[208:211], v199 offset:50176
	ds_read_b128 v[212:215], v199 offset:51200
	ds_read_b128 v[222:225], v199 offset:52224
	ds_read_b128 v[234:237], v199 offset:53248
	ds_read_b128 v[238:241], v199 offset:54272
	ds_read_b128 v[242:245], v199 offset:55296
	ds_read_b128 v[246:249], v199 offset:56320
	global_load_lds_dwordx4 v[158:159], off
	s_add_i32 m0, s27, 0x2000
	s_add_u32 s12, s12, 0x40080
	v_lshl_add_u64 v[158:159], v[250:251], 0, s[48:49]
	s_addc_u32 s13, s13, 0
	s_add_i32 s27, s85, s86
	global_load_lds_dwordx4 v[158:159], off
	v_lshl_add_u64 v[158:159], s[12:13], 0, v[130:131]
	s_mov_b32 m0, s27
	s_nop 0
	global_load_lds_dwordx4 v[158:159], off
	v_lshl_add_u64 v[158:159], s[12:13], 0, v[134:135]
	s_add_i32 m0, s27, 0x2000
	s_nop 0
	global_load_lds_dwordx4 v[158:159], off
	v_lshl_add_u64 v[158:159], v[226:227], 0, s[48:49]
	s_mov_b32 m0, s92
	s_nop 0
	global_load_lds_dwordx4 v[158:159], off
	v_lshl_add_u64 v[158:159], v[162:163], 0, s[48:49]
	s_mov_b32 m0, s93
	s_nop 0
	global_load_lds_dwordx4 v[158:159], off
	s_waitcnt vmcnt(8)
	s_waitcnt lgkmcnt(0)
	s_barrier
	s_setprio 1
	s_waitcnt lgkmcnt(0)
	v_mfma_f32_16x16x32_bf16 v[60:63], v[150:153], v[204:207], v[60:63]
	v_mfma_f32_16x16x32_bf16 v[56:59], v[170:173], v[204:207], v[56:59]
	v_mfma_f32_16x16x32_bf16 v[44:47], v[150:153], v[212:215], v[44:47]
	v_mfma_f32_16x16x32_bf16 v[40:43], v[170:173], v[212:215], v[40:43]
	v_mfma_f32_16x16x32_bf16 v[28:31], v[150:153], v[234:237], v[28:31]
	v_mfma_f32_16x16x32_bf16 v[24:27], v[170:173], v[234:237], v[24:27]
	v_mfma_f32_16x16x32_bf16 v[12:15], v[150:153], v[242:245], v[12:15]
	v_mfma_f32_16x16x32_bf16 v[8:11], v[170:173], v[242:245], v[8:11]
	v_mfma_f32_16x16x32_bf16 v[60:63], v[154:157], v[208:211], v[60:63]
	v_mfma_f32_16x16x32_bf16 v[56:59], v[174:177], v[208:211], v[56:59]
	v_mfma_f32_16x16x32_bf16 v[44:47], v[154:157], v[222:225], v[44:47]
	v_mfma_f32_16x16x32_bf16 v[40:43], v[174:177], v[222:225], v[40:43]
	v_mfma_f32_16x16x32_bf16 v[28:31], v[154:157], v[238:241], v[28:31]
	v_mfma_f32_16x16x32_bf16 v[24:27], v[174:177], v[238:241], v[24:27]
	v_mfma_f32_16x16x32_bf16 v[12:15], v[154:157], v[246:249], v[12:15]
	v_mfma_f32_16x16x32_bf16 v[8:11], v[174:177], v[246:249], v[8:11]
	s_setprio 0
	s_setprio 1
	v_mfma_f32_16x16x32_bf16 v[52:55], v[178:181], v[204:207], v[52:55]
	v_mfma_f32_16x16x32_bf16 v[48:51], v[186:189], v[204:207], v[48:51]
	v_mfma_f32_16x16x32_bf16 v[36:39], v[178:181], v[212:215], v[36:39]
	v_mfma_f32_16x16x32_bf16 v[32:35], v[186:189], v[212:215], v[32:35]
	v_mfma_f32_16x16x32_bf16 v[20:23], v[178:181], v[234:237], v[20:23]
	v_mfma_f32_16x16x32_bf16 v[16:19], v[186:189], v[234:237], v[16:19]
	v_mfma_f32_16x16x32_bf16 v[4:7], v[178:181], v[242:245], v[4:7]
	v_mfma_f32_16x16x32_bf16 v[0:3], v[186:189], v[242:245], v[0:3]
	v_mfma_f32_16x16x32_bf16 v[52:55], v[182:185], v[208:211], v[52:55]
	v_mfma_f32_16x16x32_bf16 v[48:51], v[200:203], v[208:211], v[48:51]
	v_mfma_f32_16x16x32_bf16 v[36:39], v[182:185], v[222:225], v[36:39]
	v_mfma_f32_16x16x32_bf16 v[32:35], v[200:203], v[222:225], v[32:35]
	v_mfma_f32_16x16x32_bf16 v[20:23], v[182:185], v[238:241], v[20:23]
	v_mfma_f32_16x16x32_bf16 v[16:19], v[200:203], v[238:241], v[16:19]
	v_mfma_f32_16x16x32_bf16 v[4:7], v[182:185], v[246:249], v[4:7]
	v_mfma_f32_16x16x32_bf16 v[0:3], v[200:203], v[246:249], v[0:3]
	s_setprio 0
	s_barrier
	s_add_i32 s51, s51, 2
	s_add_u32 s40, s40, 0x100
	s_addc_u32 s41, s41, 0
	s_add_u32 s25, s25, 0x100
	s_addc_u32 s50, s50, 0
	s_cmp_gt_u32 s51, 13
